# q/kv projection phase: KV tiles dealt so that workgroups carrying two Q tiles take one KV tile and the others three or four
# baseline (speedup 1.0000x reference)
; DI void phase_qkv(const Params& p, int l, char* smem) {
;     ...
;   for (int it = 0;; ++it) {
;     int tm, tn;
;     if (!tile_map(it, NTM, 8, blk__, gridDim.x, tm, tn)) break;
;     f32x4 acc[8][4]; zero_accm<8, 4>(acc);
.LBB0_712:
	s_movk_i32 s101, 26
	s_cmpk_lt_i32 s10, 38
	s_cbranch_scc0 .Lkv_many
	s_movk_i32 s101, 0x100

; DI void phase_qkv(const Params& p, int l, char* smem) {
;     ...
;   for (int it = 0;; ++it) {
;     int tm, tn;
;     if (!tile_map(it, NTM, 8, blk__, gridDim.x, tm, tn)) break;
;     f32x4 acc[8][4]; zero_accm<8, 4>(acc);
.LBB0_713:
	s_or_b64 exec, exec, s[0:1]
	s_add_i32 s10, s10, s101
	s_mov_b64 s[0:1], 0
